# v53 + windowed-attention prologue bias-table max all-reduce via DPP moves / permlane swaps instead of 6 ds_bpermute round trips
# baseline (speedup 1.0000x reference)
; #define SA_LOAD(tbase) do { const bf16* kp_ = Kp + (size_t)((tbase) + r32) * kvpitch + 8 * hi; \
;         _Pragma("unroll") for (int ks = 0; ks < 4; ++ks) kf[ks] = *(const bf16x8*)(kp_ + 16 * ks); \
;         _Pragma("unroll") for (int e = 0; e < 4; ++e) { const int c = lane + 64 * e; vr[e] = *(const v4u*)(Vp + (size_t)((tbase) + (c >> 3)) * kvpitch + (c & 7) * 8); } } while (0)
; template <int MODE> ...
;     ...
;     const int qrow = qt + (r32 >> 4), qc = qcol0 + (r32 & 15);
;     const int qtok = MODE == 0 ? qt + r32 : qrow * 64 + qc;
;     bf16x8 qf[4];
; #pragma unroll
;     for (int ks = 0; ks < 4; ++ks) qf[ks] = *(const bf16x8*)(Qb + (size_t)qtok * qpitch + 16 * ks + 8 * hi);
;     int nt, tb0, tstep, rsA = 0, kc0 = 0, my_rs = 0, my_cs = 0;
;     if (MODE == 0) { const int t0 = qt - 128 < 0 ? 0 : qt - 128; const int t1 = qt + 160 > SEQ_ ? SEQ_ : qt + 160; tb0 = t0; nt = (t1 - t0) >> 5; tstep = 32; }
;     else { rsA = qt - 4; rsA = rsA < 0 ? 0 : (rsA > 248 ? 248 : rsA); int rsB = qt - 3; rsB = rsB < 0 ? 0 : (rsB > 248 ? 248 : rsB); nt = 8 + (rsB - rsA);
;         kc0 = qcol0 - 8; kc0 = kc0 < 0 ? 0 : (kc0 > 32 ? 32 : kc0); tb0 = rsA * 64 + kc0; tstep = 64;
;         my_rs = qrow - 4; my_rs = my_rs < 0 ? 0 : (my_rs > 248 ? 248 : my_rs); my_cs = qc - 8; my_cs = my_cs < 0 ? 0 : (my_cs > 48 ? 48 : my_cs); }
;     bf16x8 kf[4]; v4u vr[4];
;     ...
;     SA_LOAD(tb0);
;     float bmx = -1e30f;
;     for (int e = lane; e < ntab; e += 64) { const float tv_ = gtab[e] * tabscale; tab[e] = tv_; bmx = fmaxf(bmx, tv_); }
; #pragma unroll
;     for (int o_ = 1; o_ < 64; o_ <<= 1) bmx = fmaxf(bmx, __shfl_xor(bmx, o_));
; __global__ void __launch_bounds__(512) mega_fwd(Args args) {
;     ...
;                 const int u = uu % 768; const int qb = u & 63, h = (u >> 6) % 6, b = u / 384; const int qt = qb * 256 + wave * 32; const size_t rb = (size_t)b * SEQ_;
;                 small_attn_wave<0>(QKV + pg8::OFF_QB + rb * 384 + h * 64, 384, QKV + pg8::OFF_KB + rb * 128 + (h / 3) * 64, QKV + pg8::OFF_VB + rb * 128 + (h / 3) * 64, 128,
;                                    YB + rb * 1024 + 256 + h * 64, qt, 0, (const float*)(ws + WS_SWB) + h * 260, 257, 1.0f, args.in[I_SINK][l * 6 + h] * LOG2E_, GSS + (size_t)(l * 3 + 1) * MT + rb, (const unsigned*)(ws + WS_KMAX) + ((l * 2 + 1) * 4 + h / 3) * 2, wl, lane);
.LBB0_464:
	s_mul_hi_i32 s0, s29, 0x2aaaaaab
	s_lshr_b32 s1, s0, 31
	s_lshr_b32 s0, s0, 7
	s_add_i32 s0, s0, s1
	s_mulk_i32 s0, 0x300
	s_sub_i32 s4, s29, s0
	s_lshr_b32 s0, s4, 6
	s_bfe_i32 s1, s0, 0x80000
	s_mul_i32 s1, s1, 43
	s_bfe_u32 s5, s1, 0x1000f
	s_bfe_u32 s1, s1, 0x80008
	s_add_i32 s1, s1, s5
	s_mul_i32 s1, s1, 6
	s_sub_i32 s30, s0, s1
	s_mul_i32 s0, s4, 0x2aab
	s_lshr_b32 s1, s0, 31
	s_ashr_i32 s0, s0, 22
	s_add_i32 s40, s0, s1
	s_lshl_b32 s0, s4, 8
	s_and_b32 s5, s0, 0x3f00
	s_add_i32 s31, s5, s11
	s_ashr_i32 s41, s40, 31
	s_mul_i32 s1, s40, 0xc00000
	v_readlane_b32 s12, v254, 3
	s_sext_i32_i8 s37, s30
	s_mul_hi_i32 s0, s40, 0xc00000
	s_add_u32 s34, s12, s1
	v_readlane_b32 s1, v254, 4
	s_addc_u32 s44, s1, s0
	s_lshl_b32 s0, s37, 6
	s_ashr_i32 s1, s0, 31
	s_lshl_b64 s[42:43], s[0:1], 1
	s_add_u32 s0, s34, s42
	s_addc_u32 s1, s44, s43
	s_lshl_b64 s[46:47], s[40:41], 22
	v_readlane_b32 s12, v254, 5
	s_add_u32 s50, s12, s46
	v_readlane_b32 s12, v254, 6
	s_addc_u32 s51, s12, s47
	s_bfe_i32 s30, s30, 0x80000
	s_mulk_i32 s30, 0x56
	s_bfe_u32 s34, s30, 0x1000f
	s_bfe_u32 s30, s30, 0x80008
	s_add_i32 s30, s30, s34
	s_sext_i32_i8 s34, s30
	s_lshl_b32 s44, s34, 6
	s_ashr_i32 s45, s44, 31
	s_lshl_b64 s[48:49], s[44:45], 1
	s_add_u32 s44, s50, s48
	s_addc_u32 s45, s51, s49
	v_readlane_b32 s12, v254, 7
	s_add_u32 s30, s12, s46
	v_readlane_b32 s12, v254, 8
	s_addc_u32 s47, s12, s47
	s_add_u32 s46, s30, s48
	s_mul_i32 s30, s60, 6
	s_addc_u32 s47, s47, s49
	s_add_i32 s50, s30, s37
	s_mul_i32 s48, s37, 0x104
	s_ashr_i32 s51, s50, 31
	s_ashr_i32 s49, s48, 31
	s_lshl_b64 s[50:51], s[50:51], 2
	s_add_u32 s50, s58, s50
	v_or_b32_e32 v124, s31, v113
	v_mov_b64_e32 v[0:1], s[0:1]
	s_movk_i32 s0, 0x300
	s_addc_u32 s51, s59, s51
	v_mad_i64_i32 v[0:1], s[0:1], v124, s0, v[0:1]
	v_lshlrev_b32_e32 v128, 1, v112
	s_max_i32 s30, s31, 0x80
	v_lshl_add_u64 v[0:1], v[0:1], 0, v[128:129]
	s_add_i32 s37, s30, 0xffffff80
	global_load_dword v168, v129, s[50:51]
	global_load_dwordx4 v[64:67], v[0:1], off
	global_load_dwordx4 v[68:71], v[0:1], off offset:32
	global_load_dwordx4 v[72:75], v[0:1], off offset:64
	global_load_dwordx4 v[76:79], v[0:1], off offset:96
	v_or_b32_e32 v0, s37, v113
	v_mov_b32_e32 v1, v129
	v_lshlrev_b64 v[0:1], 8, v[0:1]
	v_lshl_add_u64 v[0:1], s[44:45], 0, v[0:1]
	v_lshl_add_u64 v[0:1], v[0:1], 0, v[128:129]
	global_load_dwordx4 v[80:83], v[0:1], off
	global_load_dwordx4 v[84:87], v[0:1], off offset:32
	global_load_dwordx4 v[88:91], v[0:1], off offset:64
	global_load_dwordx4 v[92:95], v[0:1], off offset:96
	v_mov_b32_e32 v123, v129
	v_or_b32_e32 v0, s37, v150
	v_mov_b32_e32 v1, v129
	v_lshl_add_u64 v[126:127], s[46:47], 0, v[122:123]
	v_lshlrev_b64 v[0:1], 8, v[0:1]
	v_or_b32_e32 v2, s37, v151
	v_mov_b32_e32 v3, v129
	v_lshl_add_u64 v[0:1], v[126:127], 0, v[0:1]
	v_lshlrev_b64 v[2:3], 8, v[2:3]
	v_lshl_add_u64 v[2:3], v[126:127], 0, v[2:3]
	global_load_dwordx4 v[96:99], v[0:1], off
	global_load_dwordx4 v[100:103], v[2:3], off
	v_or_b32_e32 v0, s37, v152
	v_mov_b32_e32 v1, v129
	v_lshlrev_b64 v[0:1], 8, v[0:1]
	v_or_b32_e32 v2, s37, v153
	v_mov_b32_e32 v3, v129
	v_lshl_add_u64 v[0:1], v[126:127], 0, v[0:1]
	v_lshlrev_b64 v[2:3], 8, v[2:3]
	v_lshl_add_u64 v[2:3], v[126:127], 0, v[2:3]
	global_load_dwordx4 v[104:107], v[0:1], off
	global_load_dwordx4 v[108:111], v[2:3], off
	v_ashrrev_i32_e32 v125, 31, v124
	v_lshl_add_u64 v[0:1], s[48:49], 2, v[120:121]
	v_mov_b32_e32 v2, 0xf149f2ca
	s_movk_i32 s46, 0xc0
	global_load_dword v5, v[0:1], off
	global_load_dword v6, v[0:1], off offset:256
	global_load_dword v7, v[0:1], off offset:512
	global_load_dword v8, v[0:1], off offset:768
	s_mov_b64 s[0:1], exec
	v_cmp_eq_u32_e32 vcc, 0, v133
	s_and_b64 exec, exec, vcc
	global_load_dword v9, v[0:1], off offset:1024
	s_mov_b64 exec, s[0:1]
	s_waitcnt vmcnt(0)
	ds_write_b32 v164, v5
	ds_write_b32 v164, v6 offset:256
	ds_write_b32 v164, v7 offset:512
	ds_write_b32 v164, v8 offset:768
	v_max_f32_e32 v5, v5, v5
	v_max_f32_e32 v6, v6, v6
	v_max_f32_e32 v7, v7, v7
	v_max_f32_e32 v8, v8, v8
	v_max_f32_e32 v2, v2, v5
	v_max_f32_e32 v2, v2, v6
	v_max_f32_e32 v2, v2, v7
	v_max_f32_e32 v2, v2, v8
	s_and_b64 exec, exec, vcc
	ds_write_b32 v164, v9 offset:1024
	v_max_f32_e32 v9, v9, v9
	v_max_f32_e32 v2, v2, v9
	s_mov_b64 exec, s[0:1]
	s_add_i32 s0, s20, s34
	s_lshl_b32 s34, s0, 1
	s_lshl_b64 s[0:1], s[34:35], 2
	s_nop 1
	v_mov_b32_dpp v0, v2 quad_perm:[1,0,3,2] row_mask:0xf bank_mask:0xf
	s_add_u32 s0, s76, s0
	s_addc_u32 s1, s77, s1
	global_load_dwordx2 v[16:17], v129, s[0:1]
	v_max_f32_e32 v1, v2, v2
	s_waitcnt lgkmcnt(0)
	v_max_f32_e32 v0, v0, v0
	v_max_f32_e32 v0, v1, v0
	s_nop 1
	v_mov_b32_dpp v1, v0 quad_perm:[2,3,0,1] row_mask:0xf bank_mask:0xf
	v_and_b32_e32 v2, 0xffff0000, v65
	v_mul_f32_e32 v2, v2, v2
	s_sub_i32 s0, s30, s31
	s_sub_i32 s34, s0, 32
	s_waitcnt lgkmcnt(0)
	v_max_f32_e32 v1, v1, v1
	v_max_f32_e32 v0, v0, v1
	s_nop 1
	v_mov_b32_dpp v1, v0 row_half_mirror row_mask:0xf bank_mask:0xf
	s_mov_b64 s[0:1], -1
	s_cmpk_gt_u32 s34, 0xc0
	ds_write_b128 v166, v[96:99]
	ds_write_b128 v166, v[100:103] offset:1152
	ds_write_b128 v166, v[104:107] offset:2304
	ds_write_b128 v166, v[108:111] offset:3456
	s_waitcnt lgkmcnt(4)
	v_max_f32_e32 v1, v1, v1
	v_max_f32_e32 v0, v0, v1
	s_nop 1
	v_mov_b32_dpp v1, v0 row_mirror row_mask:0xf bank_mask:0xf
	s_waitcnt lgkmcnt(0)
	v_max_f32_e32 v1, v1, v1
	v_max_f32_e32 v0, v0, v1
	v_mov_b32_e32 v1, v0
	s_nop 1
	v_permlane16_swap_b32_e32 v1, v0
	s_waitcnt lgkmcnt(0)
; template <int MODE> ...
;     ...
;     for (int o_ = 1; o_ < 64; o_ <<= 1) bmx = fmaxf(bmx, __shfl_xor(bmx, o_));
;     float ref;
;     { float qs = 0.f;
; #pragma unroll
;       for (int ks = 0; ks < 4; ++ks) { const v4u qw = __builtin_bit_cast(v4u, qf[ks]);
; #pragma unroll
;           for (int e = 0; e < 4; ++e) { const float lo_ = __uint_as_float(qw[e] << 16), hi_ = __uint_as_float(qw[e] & 0xffff0000u); qs += lo_ * lo_ + hi_ * hi_; } }
;       auto rr = __builtin_amdgcn_permlane32_swap(__float_as_uint(qs), __float_as_uint(qs), false, false); qs = __uint_as_float(rr[0]) + __uint_as_float(rr[1]);
;       const float k2 = __uint_as_float(kmax2[0]) + __uint_as_float(kmax2[1]);
;       ref = fminf(__builtin_sqrtf(qs * k2) * 1.03f + bmx, 110.0f); }
	v_max_f32_e32 v1, v1, v1
	v_max_f32_e32 v18, v0, v1
	v_and_b32_e32 v1, 0xffff0000, v64
	v_lshlrev_b32_e32 v0, 16, v64
	v_mul_f32_e32 v1, v1, v1
	v_fmac_f32_e32 v1, v0, v0
	v_lshlrev_b32_e32 v0, 16, v65
	v_fmac_f32_e32 v2, v0, v0
	v_add_f32_e32 v0, v1, v2
	v_and_b32_e32 v2, 0xffff0000, v66
	v_lshlrev_b32_e32 v1, 16, v66
	v_mul_f32_e32 v2, v2, v2
	v_fmac_f32_e32 v2, v1, v1
	v_add_f32_e32 v0, v2, v0
	v_and_b32_e32 v2, 0xffff0000, v67
	v_lshlrev_b32_e32 v1, 16, v67
	v_mul_f32_e32 v2, v2, v2
	v_fmac_f32_e32 v2, v1, v1
	v_add_f32_e32 v0, v2, v0
	v_and_b32_e32 v2, 0xffff0000, v68
	v_lshlrev_b32_e32 v1, 16, v68
	v_mul_f32_e32 v2, v2, v2
	v_fmac_f32_e32 v2, v1, v1
	v_add_f32_e32 v0, v2, v0
	v_and_b32_e32 v2, 0xffff0000, v69
	v_lshlrev_b32_e32 v1, 16, v69
	v_mul_f32_e32 v2, v2, v2
	v_fmac_f32_e32 v2, v1, v1
	v_add_f32_e32 v0, v2, v0
	v_and_b32_e32 v2, 0xffff0000, v70
	v_lshlrev_b32_e32 v1, 16, v70
	v_mul_f32_e32 v2, v2, v2
	v_fmac_f32_e32 v2, v1, v1
	v_add_f32_e32 v0, v2, v0
	v_and_b32_e32 v2, 0xffff0000, v71
	v_lshlrev_b32_e32 v1, 16, v71
	v_mul_f32_e32 v2, v2, v2
	v_fmac_f32_e32 v2, v1, v1
	v_add_f32_e32 v0, v2, v0
	v_and_b32_e32 v2, 0xffff0000, v72
	v_lshlrev_b32_e32 v1, 16, v72
	v_mul_f32_e32 v2, v2, v2
	v_fmac_f32_e32 v2, v1, v1
	v_add_f32_e32 v0, v2, v0
	v_and_b32_e32 v2, 0xffff0000, v73
	v_lshlrev_b32_e32 v1, 16, v73
	v_mul_f32_e32 v2, v2, v2
	v_fmac_f32_e32 v2, v1, v1
	v_add_f32_e32 v0, v2, v0
	v_and_b32_e32 v2, 0xffff0000, v74
	v_lshlrev_b32_e32 v1, 16, v74
	v_mul_f32_e32 v2, v2, v2
	v_fmac_f32_e32 v2, v1, v1
	v_add_f32_e32 v0, v2, v0
	v_and_b32_e32 v2, 0xffff0000, v75
	v_lshlrev_b32_e32 v1, 16, v75
	v_mul_f32_e32 v2, v2, v2
	v_fmac_f32_e32 v2, v1, v1
	v_add_f32_e32 v0, v2, v0
	v_and_b32_e32 v2, 0xffff0000, v76
	v_lshlrev_b32_e32 v1, 16, v76
	v_mul_f32_e32 v2, v2, v2
	v_fmac_f32_e32 v2, v1, v1
	v_add_f32_e32 v0, v2, v0
	v_and_b32_e32 v2, 0xffff0000, v77
	v_lshlrev_b32_e32 v1, 16, v77
	v_mul_f32_e32 v2, v2, v2
	v_fmac_f32_e32 v2, v1, v1
	v_add_f32_e32 v0, v2, v0
	v_and_b32_e32 v2, 0xffff0000, v78
	v_lshlrev_b32_e32 v1, 16, v78
	v_mul_f32_e32 v2, v2, v2
	v_fmac_f32_e32 v2, v1, v1
	v_add_f32_e32 v0, v2, v0
	v_and_b32_e32 v2, 0xffff0000, v79
	v_mov_b32_e32 v19, v18
	s_nop 1
	v_permlane32_swap_b32_e32 v19, v18
	v_lshlrev_b32_e32 v1, 16, v79
	v_mul_f32_e32 v2, v2, v2
	v_fmac_f32_e32 v2, v1, v1
	v_add_f32_e32 v20, v2, v0
	v_mov_b32_e32 v21, v20
	s_nop 1
	v_permlane32_swap_b32_e32 v20, v21
	s_cbranch_scc0 .LBB0_500
	v_sub_u32_e32 v0, s37, v124
	v_add_u32_e32 v22, v0, v116
	v_add_u32_e32 v0, 0x80, v22
	v_cmp_gt_u32_e32 vcc, s33, v0
	v_mov_b32_e32 v1, 0xf149f2ca
	v_mov_b32_e32 v0, 0xf149f2ca
	s_and_saveexec_b64 s[0:1], vcc
	v_sub_u32_e32 v0, s30, v124
	v_add_u32_e32 v0, v0, v143
	v_lshl_add_u32 v0, v0, 2, s8
	ds_read_b32 v0, v0 offset:8704
	s_or_b64 exec, exec, s[0:1]
	v_add_u32_e32 v2, 0x81, v22
	v_cmp_gt_u32_e32 vcc, s33, v2
	s_and_saveexec_b64 s[0:1], vcc
	v_sub_u32_e32 v1, s30, v124
	v_add_u32_e32 v1, v1, v144
	v_lshl_add_u32 v1, v1, 2, s8
	ds_read_b32 v1, v1 offset:8704
	s_or_b64 exec, exec, s[0:1]
	v_add_u32_e32 v2, 0x82, v22
	v_cmp_gt_u32_e32 vcc, s33, v2
	v_mov_b32_e32 v3, 0xf149f2ca
	v_mov_b32_e32 v2, 0xf149f2ca
	s_and_saveexec_b64 s[0:1], vcc
	v_sub_u32_e32 v2, s30, v124
	v_add_u32_e32 v2, v2, v145
	v_lshl_add_u32 v2, v2, 2, s8
	ds_read_b32 v2, v2 offset:8704
	s_or_b64 exec, exec, s[0:1]
	v_add_u32_e32 v4, 0x83, v22
	v_cmp_gt_u32_e32 vcc, s33, v4
	s_and_saveexec_b64 s[0:1], vcc
	v_sub_u32_e32 v3, s30, v124
	v_add_u32_e32 v3, v3, v146
	v_lshl_add_u32 v3, v3, 2, s8
	ds_read_b32 v3, v3 offset:8704
	s_or_b64 exec, exec, s[0:1]
	v_add_u32_e32 v4, 0x88, v22
	v_cmp_gt_u32_e32 vcc, s33, v4
	v_mov_b32_e32 v5, 0xf149f2ca
	v_mov_b32_e32 v4, 0xf149f2ca
	s_and_saveexec_b64 s[0:1], vcc
	v_sub_u32_e32 v4, s30, v124
	v_add_u32_e32 v4, v4, v147
	v_lshl_add_u32 v4, v4, 2, s8
	ds_read_b32 v4, v4 offset:8704
	s_or_b64 exec, exec, s[0:1]
	v_add_u32_e32 v6, 0x89, v22
	v_cmp_gt_u32_e32 vcc, s33, v6
	s_and_saveexec_b64 s[0:1], vcc
	v_sub_u32_e32 v5, s30, v124
	v_add_u32_e32 v5, v5, v148
	v_lshl_add_u32 v5, v5, 2, s8
	ds_read_b32 v5, v5 offset:8704
	s_or_b64 exec, exec, s[0:1]
	v_add_u32_e32 v6, 0x8a, v22
	v_cmp_gt_u32_e32 vcc, s33, v6
	v_mov_b32_e32 v7, 0xf149f2ca
	v_mov_b32_e32 v6, 0xf149f2ca
	s_and_saveexec_b64 s[0:1], vcc
	v_sub_u32_e32 v6, s30, v124
	v_add_u32_e32 v6, v6, v149
	v_lshl_add_u32 v6, v6, 2, s8
	ds_read_b32 v6, v6 offset:8704
	s_or_b64 exec, exec, s[0:1]
	v_add_u32_e32 v8, 0x8b, v22
	v_cmp_gt_u32_e32 vcc, s33, v8
	s_and_saveexec_b64 s[0:1], vcc
	v_sub_u32_e32 v7, s30, v124
	v_add_u32_e32 v7, v7, v155
	v_lshl_add_u32 v7, v7, 2, s8
	ds_read_b32 v7, v7 offset:8704
	s_or_b64 exec, exec, s[0:1]
	v_add_u32_e32 v8, 0x90, v22
	v_cmp_gt_u32_e32 vcc, s33, v8
	v_mov_b32_e32 v9, 0xf149f2ca
	v_mov_b32_e32 v8, 0xf149f2ca
	s_and_saveexec_b64 s[0:1], vcc
	v_sub_u32_e32 v8, s30, v124
	v_add_u32_e32 v8, v8, v156
	v_lshl_add_u32 v8, v8, 2, s8
	ds_read_b32 v8, v8 offset:8704
	s_or_b64 exec, exec, s[0:1]
	v_add_u32_e32 v10, 0x91, v22
	v_cmp_gt_u32_e32 vcc, s33, v10
	s_and_saveexec_b64 s[0:1], vcc
	v_sub_u32_e32 v9, s30, v124
	v_add_u32_e32 v9, v9, v157
	v_lshl_add_u32 v9, v9, 2, s8
	ds_read_b32 v9, v9 offset:8704
	s_or_b64 exec, exec, s[0:1]
	v_add_u32_e32 v10, 0x92, v22
	v_cmp_gt_u32_e32 vcc, s33, v10
	v_mov_b32_e32 v11, 0xf149f2ca
	v_mov_b32_e32 v10, 0xf149f2ca
	s_and_saveexec_b64 s[0:1], vcc
	v_sub_u32_e32 v10, s30, v124
	v_add_u32_e32 v10, v10, v158
	v_lshl_add_u32 v10, v10, 2, s8
	ds_read_b32 v10, v10 offset:8704
	s_or_b64 exec, exec, s[0:1]
	v_add_u32_e32 v12, 0x93, v22
	v_cmp_gt_u32_e32 vcc, s33, v12
	s_and_saveexec_b64 s[0:1], vcc
	v_sub_u32_e32 v11, s30, v124
	v_add_u32_e32 v11, v11, v159
	v_lshl_add_u32 v11, v11, 2, s8
	ds_read_b32 v11, v11 offset:8704
	s_or_b64 exec, exec, s[0:1]
	v_add_u32_e32 v12, 0x98, v22
	v_cmp_gt_u32_e32 vcc, s33, v12
	v_mov_b32_e32 v13, 0xf149f2ca
	v_mov_b32_e32 v12, 0xf149f2ca
	s_and_saveexec_b64 s[0:1], vcc
	v_sub_u32_e32 v12, s30, v124
	v_add_u32_e32 v12, v12, v160
	v_lshl_add_u32 v12, v12, 2, s8
	ds_read_b32 v12, v12 offset:8704
	s_or_b64 exec, exec, s[0:1]
	v_add_u32_e32 v14, 0x99, v22
	v_cmp_gt_u32_e32 vcc, s33, v14
	s_and_saveexec_b64 s[0:1], vcc
	v_sub_u32_e32 v13, s30, v124
	v_add_u32_e32 v13, v13, v161
	v_lshl_add_u32 v13, v13, 2, s8
	ds_read_b32 v13, v13 offset:8704
	s_or_b64 exec, exec, s[0:1]
	v_add_u32_e32 v14, 0x9a, v22
	v_cmp_gt_u32_e32 vcc, s33, v14
	v_mov_b32_e32 v15, 0xf149f2ca
	v_mov_b32_e32 v14, 0xf149f2ca
	s_and_saveexec_b64 s[0:1], vcc
	v_sub_u32_e32 v14, s30, v124
	v_add_u32_e32 v14, v14, v162
	v_lshl_add_u32 v14, v14, 2, s8
	ds_read_b32 v14, v14 offset:8704
	s_or_b64 exec, exec, s[0:1]
	v_add_u32_e32 v22, 0x9b, v22
	v_cmp_gt_u32_e32 vcc, s33, v22
	s_and_saveexec_b64 s[0:1], vcc
	v_sub_u32_e32 v15, s30, v124
	v_add_u32_e32 v15, v15, v163
	v_lshl_add_u32 v15, v15, 2, s8
	ds_read_b32 v15, v15 offset:8704
	s_or_b64 exec, exec, s[0:1]
	s_mov_b64 s[0:1], 0

; #define SA_LOAD(tbase) do { const bf16* kp_ = Kp + (size_t)((tbase) + r32) * kvpitch + 8 * hi; \
;         _Pragma("unroll") for (int ks = 0; ks < 4; ++ks) kf[ks] = *(const bf16x8*)(kp_ + 16 * ks); \
;         _Pragma("unroll") for (int e = 0; e < 4; ++e) { const int c = lane + 64 * e; vr[e] = *(const v4u*)(Vp + (size_t)((tbase) + (c >> 3)) * kvpitch + (c & 7) * 8); } } while (0)
; template <int MODE> ...
;     ...
;     for (int ks = 0; ks < 4; ++ks) qf[ks] = *(const bf16x8*)(Qb + (size_t)qtok * qpitch + 16 * ks + 8 * hi);
;     int nt, tb0, tstep, rsA = 0, kc0 = 0, my_rs = 0, my_cs = 0;
;     if (MODE == 0) { const int t0 = qt - 128 < 0 ? 0 : qt - 128; const int t1 = qt + 160 > SEQ_ ? SEQ_ : qt + 160; tb0 = t0; nt = (t1 - t0) >> 5; tstep = 32; }
;     else { rsA = qt - 4; rsA = rsA < 0 ? 0 : (rsA > 248 ? 248 : rsA); int rsB = qt - 3; rsB = rsB < 0 ? 0 : (rsB > 248 ? 248 : rsB); nt = 8 + (rsB - rsA);
;         kc0 = qcol0 - 8; kc0 = kc0 < 0 ? 0 : (kc0 > 32 ? 32 : kc0); tb0 = rsA * 64 + kc0; tstep = 64;
;         my_rs = qrow - 4; my_rs = my_rs < 0 ? 0 : (my_rs > 248 ? 248 : my_rs); my_cs = qc - 8; my_cs = my_cs < 0 ? 0 : (my_cs > 48 ? 48 : my_cs); }
;     bf16x8 kf[4]; v4u vr[4];
;     ...
;     SA_LOAD(tb0);
;     float bmx = -1e30f;
;     for (int e = lane; e < ntab; e += 64) { const float tv_ = gtab[e] * tabscale; tab[e] = tv_; bmx = fmaxf(bmx, tv_); }
; #pragma unroll
;     for (int o_ = 1; o_ < 64; o_ <<= 1) bmx = fmaxf(bmx, __shfl_xor(bmx, o_));
; __global__ void __launch_bounds__(512) mega_fwd(Args args) {
;     ...
;                 const int u = uu & 511; const int qb = u & 63, h = (u >> 6) & 3, b = u >> 8; const size_t rb = (size_t)b * SEQ_;
;                 small_attn_wave<1>(QKV + pg8::OFF_QA + rb * 256 + h * 64, 256, QKV + pg8::OFF_KA + rb * 256 + h * 64, QKV + pg8::OFF_VA + rb * 256 + h * 64, 256,
;                                    YB + rb * 1024 + h * 64, qb * 4 + 2 * (wave >> 2), 16 * (wave & 3), args.in[I_RPB] + (size_t)(l * 4 + h) * 465, 465, LOG2E_, 0.f, GSS + (size_t)(l * 3 + 0) * MT + rb, (const unsigned*)(ws + WS_KMAX) + ((l * 2 + 0) * 4 + h) * 2, wl, lane);
.LBB0_595:
	s_bfe_u32 s37, s15, 0x20006
	v_readlane_b32 s4, v255, 14
	s_mul_i32 s0, s37, 0x1d1
	s_mul_i32 s1, s4, 0x744
	s_add_i32 s34, s1, s0
	s_lshl_b32 s0, s15, 6
	s_and_b32 s20, s0, 0x4000
	s_lshr_b32 s30, s15, 6
	s_lshl_b32 s29, s20, 9
	s_add_u32 s0, s2, s29
	s_addc_u32 s1, s3, 0
	s_lshl_b32 s21, s37, 6
	s_lshl_b32 s31, s37, 7
	v_readlane_b32 s5, v255, 15
	s_add_u32 s4, s0, s31
	s_addc_u32 s5, s1, 0
	v_readlane_b32 s0, v254, 11
	s_add_u32 s0, s0, s29
	v_readlane_b32 s1, v254, 12
	s_addc_u32 s1, s1, 0
	s_add_u32 s0, s0, s31
	s_addc_u32 s1, s1, 0
	v_readlane_b32 s12, v254, 13
	s_add_u32 s29, s12, s29
	v_readlane_b32 s12, v254, 14
	v_lshl_add_u64 v[0:1], s[34:35], 2, v[118:119]
	s_addc_u32 s34, s12, 0
	s_add_u32 s74, s29, s31
	s_addc_u32 s75, s34, 0
	s_lshl_b32 s29, s15, 2
	s_and_b32 s29, s29, 0xfc
	s_add_i32 s29, s29, s10
	v_or_b32_e32 v2, s29, v121
	v_lshl_or_b32 v116, v2, 6, v123
	v_ashrrev_i32_e32 v117, 31, v116
	v_lshlrev_b64 v[4:5], 9, v[116:117]
	v_lshl_add_u64 v[4:5], s[4:5], 0, v[4:5]
	v_lshlrev_b32_e32 v16, 1, v112
	v_mov_b32_e32 v17, v129
	v_med3_i32 v3, s29, 4, v233
	v_lshl_add_u64 v[4:5], v[4:5], 0, v[16:17]
	v_readfirstlane_b32 s31, v3
	v_add_u32_e32 v3, -4, v3
	global_load_dwordx4 v[64:67], v[4:5], off
	global_load_dwordx4 v[68:71], v[4:5], off offset:32
	global_load_dwordx4 v[72:75], v[4:5], off offset:64
	global_load_dwordx4 v[76:79], v[4:5], off offset:96
	v_lshlrev_b32_e32 v4, 6, v3
	v_add_u32_e32 v22, v155, v4
	v_add_u32_e32 v4, v22, v113
	v_mov_b32_e32 v5, v129
	v_lshlrev_b64 v[4:5], 9, v[4:5]
	v_lshl_add_u64 v[4:5], s[0:1], 0, v[4:5]
	v_lshl_add_u64 v[4:5], v[4:5], 0, v[16:17]
	global_load_dwordx4 v[80:83], v[4:5], off
	global_load_dwordx4 v[84:87], v[4:5], off offset:32
	global_load_dwordx4 v[88:91], v[4:5], off offset:64
	global_load_dwordx4 v[92:95], v[4:5], off offset:96
	v_mov_b32_e32 v115, v129
	v_or_b32_e32 v4, v22, v150
	v_mov_b32_e32 v5, v129
	v_lshl_add_u64 v[18:19], s[74:75], 0, v[114:115]
	v_lshlrev_b64 v[4:5], 9, v[4:5]
	v_lshl_add_u64 v[4:5], v[18:19], 0, v[4:5]
	global_load_dwordx4 v[96:99], v[4:5], off
	v_add_u32_e32 v4, v22, v151
	v_mov_b32_e32 v5, v129
	v_lshlrev_b64 v[4:5], 9, v[4:5]
	v_lshl_add_u64 v[4:5], v[18:19], 0, v[4:5]
	global_load_dwordx4 v[100:103], v[4:5], off
	v_add_u32_e32 v4, v22, v152
	v_mov_b32_e32 v5, v129
	v_lshlrev_b64 v[4:5], 9, v[4:5]
	v_lshl_add_u64 v[4:5], v[18:19], 0, v[4:5]
	global_load_dwordx4 v[104:107], v[4:5], off
	v_add_u32_e32 v4, v22, v153
	v_mov_b32_e32 v5, v129
	v_lshlrev_b64 v[4:5], 9, v[4:5]
	v_lshl_add_u64 v[4:5], v[18:19], 0, v[4:5]
	global_load_dwordx4 v[108:111], v[4:5], off
	v_mov_b32_e32 v4, 0xf149f2ca
	s_movk_i32 s34, 0x190
	global_load_dword v7, v[0:1], off
	global_load_dword v8, v[0:1], off offset:256
	global_load_dword v9, v[0:1], off offset:512
	global_load_dword v10, v[0:1], off offset:768
	global_load_dword v11, v[0:1], off offset:1024
	global_load_dword v12, v[0:1], off offset:1280
	global_load_dword v13, v[0:1], off offset:1536
	s_mov_b64 s[4:5], exec
	v_cmp_gt_u32_e32 vcc, 17, v133
	s_and_b64 exec, exec, vcc
	global_load_dword v14, v[0:1], off offset:1792
	s_mov_b64 exec, s[4:5]
	s_waitcnt vmcnt(0)
	v_mul_f32_e32 v7, 0x3fb8aa3b, v7
	v_mul_f32_e32 v8, 0x3fb8aa3b, v8
	v_mul_f32_e32 v9, 0x3fb8aa3b, v9
	v_mul_f32_e32 v10, 0x3fb8aa3b, v10
	v_mul_f32_e32 v11, 0x3fb8aa3b, v11
	v_mul_f32_e32 v12, 0x3fb8aa3b, v12
	v_mul_f32_e32 v13, 0x3fb8aa3b, v13
	ds_write_b32 v162, v7
	ds_write_b32 v162, v8 offset:256
	ds_write_b32 v162, v9 offset:512
	ds_write_b32 v162, v10 offset:768
	ds_write_b32 v162, v11 offset:1024
	ds_write_b32 v162, v12 offset:1280
	ds_write_b32 v162, v13 offset:1536
	v_max_f32_e32 v4, v4, v7
	v_max_f32_e32 v4, v4, v8
	v_max_f32_e32 v4, v4, v9
	v_max_f32_e32 v4, v4, v10
	v_max_f32_e32 v4, v4, v11
	v_max_f32_e32 v4, v4, v12
	v_max_f32_e32 v4, v4, v13
	s_and_b64 exec, exec, vcc
	v_mul_f32_e32 v14, 0x3fb8aa3b, v14
	ds_write_b32 v162, v14 offset:1792
	v_max_f32_e32 v4, v4, v14
	s_mov_b64 exec, s[4:5]
	s_lshl_b32 s4, s37, 1
	s_or_b32 s34, s4, s9
	s_lshl_b64 s[4:5], s[34:35], 2
	s_nop 1
	v_mov_b32_dpp v1, v4 quad_perm:[1,0,3,2] row_mask:0xf bank_mask:0xf
	s_add_u32 s74, s76, s4
	s_addc_u32 s75, s77, s5
	global_load_dwordx2 v[20:21], v129, s[74:75]
	v_max_f32_e32 v4, v4, v4
	s_waitcnt lgkmcnt(0)
	v_max_f32_e32 v1, v1, v1
	v_max_f32_e32 v1, v4, v1
	s_nop 1
	v_mov_b32_dpp v4, v1 quad_perm:[2,3,0,1] row_mask:0xf bank_mask:0xf
	v_and_b32_e32 v5, 0xffff0000, v65
	v_mul_f32_e32 v5, v5, v5
	v_med3_i32 v0, v2, 4, v233
	v_sub_u32_e32 v0, s31, v0
	s_waitcnt lgkmcnt(0)
	v_max_f32_e32 v4, v4, v4
	v_max_f32_e32 v1, v1, v4
	s_nop 1
	v_mov_b32_dpp v4, v1 row_half_mirror row_mask:0xf bank_mask:0xf
	v_cmp_gt_u32_e32 vcc, 8, v0
	v_sub_u32_e32 v0, v3, v2
	s_and_b64 s[74:75], vcc, s[38:39]
	ds_write_b128 v186, v[96:99]
	ds_write_b128 v186, v[100:103] offset:1152
	ds_write_b128 v186, v[104:107] offset:2304
	ds_write_b128 v186, v[108:111] offset:3456
	s_waitcnt lgkmcnt(4)
	v_max_f32_e32 v4, v4, v4
	v_max_f32_e32 v1, v1, v4
	s_nop 1
	v_mov_b32_dpp v4, v1 row_mirror row_mask:0xf bank_mask:0xf
	s_waitcnt lgkmcnt(0)
	v_max_f32_e32 v4, v4, v4
	v_max_f32_e32 v1, v1, v4
	v_mov_b32_e32 v4, v1
	s_nop 1
	v_permlane16_swap_b32_e32 v4, v1
	s_waitcnt lgkmcnt(0)
; #define LAS __attribute__((address_space(3)))
; #define SA_LOAD(tbase) do { const bf16* kp_ = Kp + (size_t)((tbase) + r32) * kvpitch + 8 * hi; \
;         _Pragma("unroll") for (int ks = 0; ks < 4; ++ks) kf[ks] = *(const bf16x8*)(kp_ + 16 * ks); \
;         _Pragma("unroll") for (int e = 0; e < 4; ++e) { const int c = lane + 64 * e; vr[e] = *(const v4u*)(Vp + (size_t)((tbase) + (c >> 3)) * kvpitch + (c & 7) * 8); } } while (0)
; #define SA_VWRITE(buf) do { _Pragma("unroll") for (int e = 0; e < 4; ++e) { const int c = lane + 64 * e; *(LAS v4u*)(wl + (buf) * 4608 + (c >> 3) * 144 + (c & 7) * 16) = vr[e]; } } while (0)
; #define SA_QK(X) do { _Pragma("unroll") for (int ks = 0; ks < 4; ++ks) X = __builtin_amdgcn_mfma_f32_32x32x16_bf16(kf[ks], qf[ks], X, 0, 0, 0); } while (0)
; template <int MODE> ...
;     ...
;     for (int o_ = 1; o_ < 64; o_ <<= 1) bmx = fmaxf(bmx, __shfl_xor(bmx, o_));
;     float ref;
;     { float qs = 0.f;
; #pragma unroll
;       for (int ks = 0; ks < 4; ++ks) { const v4u qw = __builtin_bit_cast(v4u, qf[ks]);
; #pragma unroll
;           for (int e = 0; e < 4; ++e) { const float lo_ = __uint_as_float(qw[e] << 16), hi_ = __uint_as_float(qw[e] & 0xffff0000u); qs += lo_ * lo_ + hi_ * hi_; } }
;       auto rr = __builtin_amdgcn_permlane32_swap(__float_as_uint(qs), __float_as_uint(qs), false, false); qs = __uint_as_float(rr[0]) + __uint_as_float(rr[1]);
;       const float k2 = __uint_as_float(kmax2[0]) + __uint_as_float(kmax2[1]);
;       ref = fminf(__builtin_sqrtf(qs * k2) * 1.03f + bmx, 110.0f); }
;     f32x16 o0 = {}, o1 = {};
;     float lsum = 0.f;
;     const int i16 = lane & 15, g16 = (lane >> 4) & 1;
;     LAS unsigned char* vaddr = wl + (4 * hi + (i16 >> 2)) * 144 + g16 * 32 + 8 * (i16 & 3);
;     f32x16 xa_, xb_;
;     SA_VWRITE(0); SA_CINIT(0, xa_); SA_QK(xa_);
;     if (nt > 1) SA_LOAD(tb0 + tstep);
	v_max_f32_e32 v4, v4, v4
	v_max_f32_e32 v23, v1, v4
	v_and_b32_e32 v4, 0xffff0000, v64
	v_lshlrev_b32_e32 v1, 16, v64
	v_mul_f32_e32 v4, v4, v4
	v_fmac_f32_e32 v4, v1, v1
	v_lshlrev_b32_e32 v1, 16, v65
	v_fmac_f32_e32 v5, v1, v1
	v_add_f32_e32 v1, v4, v5
	v_and_b32_e32 v5, 0xffff0000, v66
	v_lshlrev_b32_e32 v4, 16, v66
	v_mul_f32_e32 v5, v5, v5
	v_fmac_f32_e32 v5, v4, v4
	v_add_f32_e32 v1, v5, v1
	v_and_b32_e32 v5, 0xffff0000, v67
	v_lshlrev_b32_e32 v4, 16, v67
	v_mul_f32_e32 v5, v5, v5
	v_fmac_f32_e32 v5, v4, v4
	v_add_f32_e32 v1, v5, v1
	v_and_b32_e32 v5, 0xffff0000, v68
	v_lshlrev_b32_e32 v4, 16, v68
	v_mul_f32_e32 v5, v5, v5
	v_fmac_f32_e32 v5, v4, v4
	v_add_f32_e32 v1, v5, v1
	v_and_b32_e32 v5, 0xffff0000, v69
	v_lshlrev_b32_e32 v4, 16, v69
	v_mul_f32_e32 v5, v5, v5
	v_fmac_f32_e32 v5, v4, v4
	v_add_f32_e32 v1, v5, v1
	v_and_b32_e32 v5, 0xffff0000, v70
	v_lshlrev_b32_e32 v4, 16, v70
	v_mul_f32_e32 v5, v5, v5
	v_fmac_f32_e32 v5, v4, v4
	v_add_f32_e32 v1, v5, v1
	v_and_b32_e32 v5, 0xffff0000, v71
	v_lshlrev_b32_e32 v4, 16, v71
	v_mul_f32_e32 v5, v5, v5
	v_fmac_f32_e32 v5, v4, v4
	v_add_f32_e32 v1, v5, v1
	v_and_b32_e32 v5, 0xffff0000, v72
	v_lshlrev_b32_e32 v4, 16, v72
	v_mul_f32_e32 v5, v5, v5
	v_fmac_f32_e32 v5, v4, v4
	v_add_f32_e32 v1, v5, v1
	v_and_b32_e32 v5, 0xffff0000, v73
	v_lshlrev_b32_e32 v4, 16, v73
	v_mul_f32_e32 v5, v5, v5
	v_fmac_f32_e32 v5, v4, v4
	v_add_f32_e32 v1, v5, v1
	v_and_b32_e32 v5, 0xffff0000, v74
	v_lshlrev_b32_e32 v4, 16, v74
	v_mul_f32_e32 v5, v5, v5
	v_fmac_f32_e32 v5, v4, v4
	v_add_f32_e32 v1, v5, v1
	v_and_b32_e32 v5, 0xffff0000, v75
	v_lshlrev_b32_e32 v4, 16, v75
	v_mul_f32_e32 v5, v5, v5
	v_fmac_f32_e32 v5, v4, v4
	v_add_f32_e32 v1, v5, v1
	v_and_b32_e32 v5, 0xffff0000, v76
	v_lshlrev_b32_e32 v4, 16, v76
	v_mul_f32_e32 v5, v5, v5
	v_fmac_f32_e32 v5, v4, v4
	v_add_f32_e32 v1, v5, v1
	v_and_b32_e32 v5, 0xffff0000, v77
	v_lshlrev_b32_e32 v4, 16, v77
	v_mul_f32_e32 v5, v5, v5
	v_fmac_f32_e32 v5, v4, v4
	v_add_f32_e32 v1, v5, v1
	v_and_b32_e32 v5, 0xffff0000, v78
	v_lshlrev_b32_e32 v4, 16, v78
	v_mul_f32_e32 v5, v5, v5
	v_fmac_f32_e32 v5, v4, v4
	v_add_f32_e32 v1, v5, v1
	v_and_b32_e32 v5, 0xffff0000, v79
	v_mov_b32_e32 v24, v23
	s_nop 1
	v_permlane32_swap_b32_e32 v24, v23
	v_lshlrev_b32_e32 v4, 16, v79
	v_mul_f32_e32 v5, v5, v5
	v_fmac_f32_e32 v5, v4, v4
	v_add_f32_e32 v25, v5, v1
	v_mad_u64_u32 v[0:1], s[4:5], v0, 31, v[120:121]
	v_mov_b32_e32 v26, v25
	v_cndmask_b32_e32 v0, 0, v0, vcc
	s_nop 0
	v_permlane32_swap_b32_e32 v25, v26
	v_lshl_add_u32 v17, v0, 2, s8
	v_mov_b32_e32 v1, 0xf149f2ca
	v_mov_b32_e32 v0, 0xf149f2ca
	s_and_saveexec_b64 s[4:5], s[74:75]
	ds_read_b32 v0, v17 offset:9216
	s_or_b64 exec, exec, s[4:5]
	s_and_b64 s[74:75], vcc, s[40:41]
	s_and_saveexec_b64 s[4:5], s[74:75]
	ds_read_b32 v1, v17 offset:9220
	s_or_b64 exec, exec, s[4:5]
	s_and_b64 s[74:75], vcc, s[42:43]
	v_mov_b32_e32 v3, 0xf149f2ca
	v_mov_b32_e32 v2, 0xf149f2ca
	s_and_saveexec_b64 s[4:5], s[74:75]
	ds_read_b32 v2, v17 offset:9224
	s_or_b64 exec, exec, s[4:5]
	s_and_b64 s[74:75], vcc, s[44:45]
	s_and_saveexec_b64 s[4:5], s[74:75]
	ds_read_b32 v3, v17 offset:9228
	s_or_b64 exec, exec, s[4:5]
	s_and_b64 s[74:75], vcc, s[46:47]
	v_mov_b32_e32 v5, 0xf149f2ca
	v_mov_b32_e32 v4, 0xf149f2ca
	s_and_saveexec_b64 s[4:5], s[74:75]
	ds_read_b32 v4, v17 offset:9248
	s_or_b64 exec, exec, s[4:5]
	s_and_b64 s[74:75], vcc, s[48:49]
	s_and_saveexec_b64 s[4:5], s[74:75]
	ds_read_b32 v5, v17 offset:9252
	s_or_b64 exec, exec, s[4:5]
	s_and_b64 s[74:75], vcc, s[50:51]
	v_mov_b32_e32 v7, 0xf149f2ca
	v_mov_b32_e32 v6, 0xf149f2ca
	s_and_saveexec_b64 s[4:5], s[74:75]
	ds_read_b32 v6, v17 offset:9256
	s_or_b64 exec, exec, s[4:5]
	s_and_b64 s[74:75], vcc, s[52:53]
	s_and_saveexec_b64 s[4:5], s[74:75]
	ds_read_b32 v7, v17 offset:9260
	s_or_b64 exec, exec, s[4:5]
	s_and_b64 s[74:75], vcc, s[54:55]
	v_mov_b32_e32 v9, 0xf149f2ca
	v_mov_b32_e32 v8, 0xf149f2ca
	s_and_saveexec_b64 s[4:5], s[74:75]
	ds_read_b32 v8, v17 offset:9280
	s_or_b64 exec, exec, s[4:5]
	s_and_b64 s[74:75], vcc, s[56:57]
	s_and_saveexec_b64 s[4:5], s[74:75]
	ds_read_b32 v9, v17 offset:9284
	s_or_b64 exec, exec, s[4:5]
	s_and_b64 s[74:75], vcc, s[58:59]
	v_mov_b32_e32 v11, 0xf149f2ca
	v_mov_b32_e32 v10, 0xf149f2ca
	s_and_saveexec_b64 s[4:5], s[74:75]
	ds_read_b32 v10, v17 offset:9288
	s_or_b64 exec, exec, s[4:5]
	s_and_b64 s[74:75], vcc, s[60:61]
	s_and_saveexec_b64 s[4:5], s[74:75]
	ds_read_b32 v11, v17 offset:9292
	s_or_b64 exec, exec, s[4:5]
	s_and_b64 s[74:75], vcc, s[62:63]
	v_mov_b32_e32 v13, 0xf149f2ca
	v_mov_b32_e32 v12, 0xf149f2ca
	s_and_saveexec_b64 s[4:5], s[74:75]
	ds_read_b32 v12, v17 offset:9312
	s_or_b64 exec, exec, s[4:5]
	s_and_b64 s[74:75], vcc, s[64:65]
	s_and_saveexec_b64 s[4:5], s[74:75]
	ds_read_b32 v13, v17 offset:9316
	s_or_b64 exec, exec, s[4:5]
	s_and_b64 s[74:75], vcc, s[66:67]
	v_mov_b32_e32 v15, 0xf149f2ca
	v_mov_b32_e32 v14, 0xf149f2ca
	s_and_saveexec_b64 s[4:5], s[74:75]
	ds_read_b32 v14, v17 offset:9320
	s_or_b64 exec, exec, s[4:5]
	s_and_b64 s[74:75], vcc, s[68:69]
	s_and_saveexec_b64 s[4:5], s[74:75]
	ds_read_b32 v15, v17 offset:9324
	s_or_b64 exec, exec, s[4:5]
	s_waitcnt lgkmcnt(0)
	v_mfma_f32_32x32x16_bf16 v[0:15], v[80:83], v[64:67], v[0:15]
	v_med3_i32 v17, s29, 3, v234
	s_nop 0
	v_readfirstlane_b32 s4, v17
	s_sub_i32 s31, s4, s31
	s_cmp_lt_i32 s31, -7
	v_mfma_f32_32x32x16_bf16 v[0:15], v[84:87], v[68:71], v[0:15]
	v_mfma_f32_32x32x16_bf16 v[0:15], v[88:91], v[72:75], v[0:15]
	v_mfma_f32_32x32x16_bf16 v[0:15], v[92:95], v[76:79], v[0:15]
	s_cbranch_scc1 .LBB0_631
	v_add_u32_e32 v22, 64, v22
	v_add_u32_e32 v28, v22, v113
	v_mov_b32_e32 v29, v129
	v_lshlrev_b64 v[28:29], 9, v[28:29]
	v_lshl_add_u64 v[28:29], s[0:1], 0, v[28:29]
	v_mov_b32_e32 v17, v129
	v_lshl_add_u64 v[16:17], v[28:29], 0, v[16:17]
	global_load_dwordx4 v[80:83], v[16:17], off
	global_load_dwordx4 v[84:87], v[16:17], off offset:32
	global_load_dwordx4 v[88:91], v[16:17], off offset:64
	global_load_dwordx4 v[92:95], v[16:17], off offset:96
	v_or_b32_e32 v16, v22, v150
	v_mov_b32_e32 v17, v129
	v_lshlrev_b64 v[16:17], 9, v[16:17]
	v_add_u32_e32 v28, v22, v151
	v_mov_b32_e32 v29, v129
	v_lshl_add_u64 v[16:17], v[18:19], 0, v[16:17]
	v_lshlrev_b64 v[28:29], 9, v[28:29]
	v_lshl_add_u64 v[28:29], v[18:19], 0, v[28:29]
	global_load_dwordx4 v[96:99], v[16:17], off
	global_load_dwordx4 v[100:103], v[28:29], off
	v_add_u32_e32 v16, v22, v152
	v_mov_b32_e32 v17, v129
	v_lshlrev_b64 v[16:17], 9, v[16:17]
	v_add_u32_e32 v28, v22, v153
	v_mov_b32_e32 v29, v129
	v_lshl_add_u64 v[16:17], v[18:19], 0, v[16:17]
	v_lshlrev_b64 v[28:29], 9, v[28:29]
	v_lshl_add_u64 v[18:19], v[18:19], 0, v[28:29]
	global_load_dwordx4 v[104:107], v[16:17], off
	global_load_dwordx4 v[108:111], v[18:19], off
